# MLA latent-norm row loop: next token prefetched, counted vmcnt no longer waits for the previous stores
# baseline (speedup 1.0000x reference)
; __device__ __forceinline__ float opq(float v) { asm volatile("" : "+v"(v)); return v; }
; __device__ __forceinline__ unsigned pk2(float lo, float hi) { f32x2_t v = {lo, hi}; bf16x2_t b = __builtin_convertvector(v, bf16x2_t); return __builtin_bit_cast(unsigned, b); }
; __device__ __forceinline__ void post1(const KA& A, int L, LAS unsigned char* lds, int bid, int tid, int wave, int lane, int rep, int parts) {
;     ...
;     if (parts & 1) {
;         const float* gq = A.in(I_MQN) + L * 256 + 4 * lane; const float* gk = A.in(I_MKVN) + L * 128 + 2 * lane;
;         const f32x4 gqv = *(const f32x4*)gq; const float gk0 = gk[0], gk1 = gk[1];
;         for (int tok = gwb; tok < TG; tok += NGW) {
;             const bf16_t* zr = Z + (size_t)tok * NINP;
;             const u32x2 qw = *(const u32x2*)(zr + ZCQ + 4 * lane); const unsigned kw = *(const unsigned*)(zr + ZCKV + 2 * lane);
;             const float q0 = __uint_as_float(qw.x << 16), q1 = __uint_as_float(qw.x & 0xffff0000u), q2 = __uint_as_float(qw.y << 16), q3 = __uint_as_float(qw.y & 0xffff0000u);
;             const float k0 = __uint_as_float(kw << 16), k1 = __uint_as_float(kw & 0xffff0000u);
;             const float rq = rsqrtf(wave_sum((q0 * q0 + q1 * q1) + (q2 * q2 + q3 * q3), lane) * (1.f / 256.f) + opq(EPS));
;             const float rk = rsqrtf(wave_sum(k0 * k0 + k1 * k1, lane) * (1.f / 128.f) + opq(EPS));
;             u32x2 o; o.x = pk2(q0 * rq * gqv.x, q1 * rq * gqv.y); o.y = pk2(q2 * rq * gqv.z, q3 * rq * gqv.w);
;             *(u32x2*)((bf16_t*)(ws + WS_CQN) + (size_t)tok * 256 + 4 * lane) = o;
;             *(unsigned*)((bf16_t*)(ws + WS_CKVN) + (size_t)tok * 128 + 2 * lane) = pk2(k0 * rk * gk0, k1 * rk * gk1);
;         }
.LBB0_961:
	s_andn2_b64 vcc, exec, s[2:3]
	s_cbranch_vccnz .LBB0_973
	v_readlane_b32 s0, v254, 38
	s_cmp_lt_i32 s0, 2
	s_mov_b64 s[2:3], -1
	s_cbranch_scc1 .LBB0_968
	v_readlane_b32 s0, v254, 38
	s_cmp_eq_u32 s0, 2
	s_cbranch_scc0 .LBB0_967
	v_mov_b32_e32 v0, v1
	v_readlane_b32 s0, v254, 5
	s_mul_i32 s0, s0, s82
	s_add_i32 s2, s0, s79
	s_cmpk_gt_i32 s2, 0x1fff
	s_waitcnt vmcnt(0) lgkmcnt(0)
	s_barrier
	s_cbranch_scc1 .LBB0_967
	v_readlane_b32 s0, v254, 36
	v_readlane_b32 s1, v254, 37
	s_load_dwordx2 s[4:5], s[0:1], 0x30
	s_load_dwordx2 s[6:7], s[0:1], 0x40
	v_readlane_b32 s0, v254, 32
	s_lshl_b32 s8, s0, 7
	v_mbcnt_lo_u32_b32 v0, -1, v0
	s_ashr_i32 s9, s8, 31
	v_mbcnt_hi_u32_b32 v8, -1, v0
	s_lshl_b64 s[8:9], s[8:9], 2
	s_waitcnt lgkmcnt(0)
	s_add_u32 s6, s6, s8
	v_lshlrev_b32_e32 v10, 1, v8
	s_addc_u32 s7, s7, s9
	v_ashrrev_i32_e32 v11, 31, v10
	v_lshl_add_u64 v[2:3], v[10:11], 2, s[6:7]
	s_lshl_b32 s6, s0, 8
	s_ashr_i32 s7, s6, 31
	s_lshl_b64 s[6:7], s[6:7], 2
	v_lshlrev_b32_e32 v12, 2, v8
	s_add_u32 s4, s4, s6
	v_ashrrev_i32_e32 v13, 31, v12
	s_addc_u32 s5, s5, s7
	global_load_dwordx2 v[6:7], v[2:3], off
	v_lshl_add_u64 v[2:3], v[12:13], 2, s[4:5]
	global_load_dwordx4 v[2:5], v[2:3], off
	s_ashr_i32 s3, s2, 31
	s_lshl_b64 s[4:5], s[2:3], 8
	s_add_u32 s4, s90, s4
	s_addc_u32 s5, s91, s5
	v_lshl_add_u64 v[10:11], v[10:11], 1, s[4:5]
	s_mov_b64 s[4:5], 0x4c00000
	v_lshl_add_u64 v[10:11], v[10:11], 0, s[4:5]
	s_lshl_b64 s[4:5], s[2:3], 9
	s_add_u32 s4, s90, s4
	v_readlane_b32 s1, v254, 33
	v_lshlrev_b64 v[14:15], 1, v[12:13]
	s_addc_u32 s5, s91, s5
	v_xor_b32_e32 v0, 4, v12
	v_xor_b32_e32 v16, 8, v12
	v_xor_b32_e32 v17, 16, v12
	v_xor_b32_e32 v18, 32, v12
	v_xor_b32_e32 v19, 64, v12
	v_lshl_add_u64 v[12:13], s[4:5], 0, v[14:15]
	s_mov_b64 s[0:1], 0x4800000
	v_lshl_add_u64 v[12:13], v[12:13], 0, s[0:1]
	s_mul_i32 s1, s2, 0x3200
	v_ashrrev_i32_e32 v9, 31, v8
	s_mul_hi_i32 s0, s2, 0x3200
	s_add_u32 s4, s90, s1
	v_lshlrev_b64 v[8:9], 2, v[8:9]
	s_addc_u32 s5, s91, s0
	v_sub_co_u32_e32 v8, vcc, 0, v8
	v_lshl_add_u64 v[14:15], s[4:5], 0, v[14:15]
	s_mov_b64 s[4:5], 0x5800c00
	v_readlane_b32 s0, v254, 10
	v_readlane_b32 s6, v254, 21
	v_readlane_b32 s8, v254, 23
	v_subb_co_u32_e32 v9, vcc, 0, v9, vcc
	v_lshl_add_u64 v[14:15], v[14:15], 0, s[4:5]
	v_readlane_b32 s1, v254, 11
	v_readlane_b32 s7, v254, 22
	v_readlane_b32 s9, v254, 24
	global_load_dwordx2 v[40:41], v[14:15], off
	v_lshl_add_u64 v[44:45], v[14:15], 0, v[8:9]
	global_load_dword v42, v[44:45], off offset:512
	s_waitcnt vmcnt(0)
	s_branch .Lmln_body
.LBB0_966:
	s_waitcnt vmcnt(2)
.Lmln_body:
	v_mov_b32_e32 v20, v40
	v_mov_b32_e32 v21, v41
	v_mov_b32_e32 v28, v42
	s_add_i32 s2, s2, s78
	s_cmpk_gt_i32 s2, 0x1fff
	s_cbranch_scc1 .Lmln_nopf
	v_lshl_add_u64 v[14:15], v[14:15], 0, s[0:1]
	global_load_dwordx2 v[40:41], v[14:15], off
	v_lshl_add_u64 v[44:45], v[14:15], 0, v[8:9]
	global_load_dword v42, v[44:45], off offset:512
.Lmln_nopf:
	v_mov_b32_e32 v23, 0x358637bd
	v_mov_b32_e32 v22, 0x358637bd
	v_and_b32_e32 v25, 0xffff0000, v21
	v_and_b32_e32 v27, 0xffff0000, v20
	v_lshlrev_b32_e32 v24, 16, v21
	v_lshlrev_b32_e32 v26, 16, v20
	v_mov_b32_e32 v30, v27
	v_mov_b32_e32 v31, v25
	v_lshlrev_b32_e32 v20, 16, v28
	v_and_b32_e32 v21, 0xffff0000, v28
	v_mov_b32_e32 v28, v26
	v_mov_b32_e32 v29, v24
	v_pk_mul_f32 v[30:31], v[30:31], v[30:31]
	v_pk_mul_f32 v[32:33], v[20:21], v[20:21]
	v_pk_fma_f32 v[28:29], v[28:29], v[28:29], v[30:31]
	v_add_f32_e32 v30, v32, v33
	v_add_f32_e32 v28, v28, v29
	ds_bpermute_b32 v29, v0, v30
	ds_bpermute_b32 v31, v0, v28
	s_waitcnt lgkmcnt(1)
	v_add_f32_e32 v29, v30, v29
	s_waitcnt lgkmcnt(0)
	v_add_f32_e32 v28, v28, v31
	ds_bpermute_b32 v30, v16, v29
	ds_bpermute_b32 v31, v16, v28
	s_waitcnt lgkmcnt(1)
	v_add_f32_e32 v29, v29, v30
	s_waitcnt lgkmcnt(0)
	v_add_f32_e32 v28, v28, v31
	ds_bpermute_b32 v30, v17, v29
	ds_bpermute_b32 v31, v17, v28
	s_waitcnt lgkmcnt(1)
	v_add_f32_e32 v29, v29, v30
	s_waitcnt lgkmcnt(0)
	v_add_f32_e32 v28, v28, v31
	ds_bpermute_b32 v30, v18, v29
	ds_bpermute_b32 v31, v18, v28
	s_waitcnt lgkmcnt(1)
	v_add_f32_e32 v29, v29, v30
	s_waitcnt lgkmcnt(0)
	v_add_f32_e32 v30, v28, v31
	ds_bpermute_b32 v28, v19, v29
	ds_bpermute_b32 v31, v19, v30
	s_waitcnt lgkmcnt(1)
	v_add_f32_e32 v28, v29, v28
	s_waitcnt lgkmcnt(0)
	v_add_f32_e32 v29, v30, v31
	v_mov_b32_e32 v30, v28
	v_mov_b32_e32 v31, v29
	s_nop 0
	v_permlane32_swap_b32_e32 v28, v30
	v_permlane32_swap_b32_e32 v29, v31
	v_pk_add_f32 v[28:29], v[28:29], v[30:31]
	s_nop 0
	v_pk_fma_f32 v[22:23], v[28:29], s[76:77], v[22:23]
	s_nop 0
	v_mul_f32_e32 v28, 0x4b800000, v23
	v_cmp_gt_f32_e64 s[4:5], s57, v23
	v_mul_f32_e32 v29, 0x4b800000, v22
	v_cmp_gt_f32_e32 vcc, s57, v22
	v_cndmask_b32_e64 v23, v23, v28, s[4:5]
	v_rsq_f32_e32 v23, v23
	v_cndmask_b32_e32 v22, v22, v29, vcc
	v_rsq_f32_e32 v28, v22
	v_mul_f32_e32 v22, 0x45800000, v23
	v_cndmask_b32_e64 v22, v23, v22, s[4:5]
	v_mul_f32_e32 v29, 0x45800000, v28
	v_cndmask_b32_e32 v28, v28, v29, vcc
	v_pk_mul_f32 v[26:27], v[22:23], v[26:27] op_sel_hi:[0,1]
	v_pk_mul_f32 v[22:23], v[22:23], v[24:25] op_sel_hi:[0,1]
	v_pk_mul_f32 v[20:21], v[28:29], v[20:21] op_sel_hi:[0,1]
	v_pk_mul_f32 v[24:25], v[2:3], v[26:27]
	v_pk_mul_f32 v[22:23], v[4:5], v[22:23]
	v_pk_mul_f32 v[20:21], v[6:7], v[20:21]
	v_cvt_pk_bf16_f32 v24, v24, v25
	v_cvt_pk_bf16_f32 v25, v22, v23
	v_cvt_pk_bf16_f32 v20, v20, v21
	global_store_dwordx2 v[12:13], v[24:25], off
	global_store_dword v[10:11], v20, off
	v_lshl_add_u64 v[10:11], v[10:11], 0, s[6:7]
	v_lshl_add_u64 v[12:13], v[12:13], 0, s[8:9]
	s_cmpk_gt_i32 s2, 0x1fff
	s_cbranch_scc0 .LBB0_966
